# stack11 minus the three vmcnt(0) waits at the attention ticket use sites (ticket atomic is older than the Q loads, already covered by the following counted waits)
# baseline (speedup 1.0000x reference)
; #define ATT_LOAD(t, S) do { const int tl_ = (t) < u_hi ? (t) : u_hi;     \
;         k##S = *(const u32x4*)(kg + (size_t)tl_ * 64 * 512); v##S = *(const u32x4*)(vg + (size_t)tl_ * 64 * 512); \
;         if (TYPE == 1) k2##S = *(const u32x4*)(krg + (size_t)tl_ * 64 * 32); if (TYPE == 0) cb##S = cg_[tl_ * 64]; } while (0)
; template <int TYPE> __device__ __forceinline__ int unit(const P& p, LAS unsigned char* lds, int b, int h, int qb, int wave0, bool pre, unsigned nx, int G,
;         u32x4& kA, u32x4& vA, u32x4& k2A, float& cbA, u32x4& kB, u32x4& vB, u32x4& k2B, float& cbB) {
;     ...
;     float m_run = 0.f, l_run = 0.f; f32x16 o0 = {}, o1 = {};
;     f32x16 negm;
; #pragma unroll
;     for (int r = 0; r < 16; ++r) negm[r] = 0.f;
;     if (!pre) { ATT_LOAD(u_lo, A); ATT_LOAD(u_lo + 1, B); }
;     ATT_STORE(0, A);
;     __syncthreads();
;     const int qrel = 32 * (w & 1) + r32;
;     int t = u_lo;
;     for (; t < u_hi - 1; t += 2) {
;         ATT_LOAD(t + 2, A);
;         if (t >= w_lo && t <= w_hi) tile<TYPE, ND0, KSTR>(lds, 0, t, w_lo, w_hi, n, qrel, lane, r32, hi, qr, m_run, l_run, o0, o1, negm);
;         ATT_STORE(1, B);
;         __syncthreads();
;         ATT_LOAD(t + 3, B);
;         if (t + 1 >= w_lo && t + 1 <= w_hi) tile<TYPE, ND0, KSTR>(lds, 1, t + 1, w_lo, w_hi, n, qrel, lane, r32, hi, qr, m_run, l_run, o0, o1, negm);
;         ATT_STORE(0, A);
;         if (t == u_lo && tid == 0) tk[0] = G + (int)nx;
.LBB0_605:
	s_movk_i32 s4, 0x90
	v_lshlrev_b64 v[220:221], 9, v[10:11]
	v_mul_lo_u32 v10, v226, s4
	v_add_u32_e32 v10, 0, v10
	s_ashr_i32 s2, s2, 7
	v_add_u32_e32 v240, v10, v0
	v_lshrrev_b32_e32 v244, 2, v206
	s_waitcnt vmcnt(3)
	ds_write_b128 v240, v[6:9]
	v_mad_u64_u32 v[6:7], s[0:1], v226, 48, v[10:11]
	v_mad_u32_u24 v205, v242, s4, 0
	v_lshlrev_b32_e32 v218, 2, v12
	s_lshl_b32 s4, s28, 10
	s_lshl_b32 s5, s2, 8
	v_and_b32_e32 v14, 63, v206
	v_add_u32_e32 v241, v6, v0
	v_and_or_b32 v0, v244, 3, v218
	s_add_i32 s4, s4, s5
	s_lshl_b32 s5, s11, 2
	v_mad_u32_u24 v207, v0, s27, 0
	v_and_b32_e32 v0, 16, v206
	v_lshlrev_b32_e32 v224, 2, v14
	s_and_b32 s5, s5, 0x80
	v_and_or_b32 v0, v224, 12, v0
	s_or_b32 s4, s4, s5
	v_lshlrev_b32_e32 v243, 1, v0
	v_lshl_or_b32 v0, v242, 2, s4
	v_sub_u32_e32 v0, v0, v204
	s_lshl_b32 s4, s9, 8
	v_subrev_u32_e32 v0, s4, v0
	v_readlane_b32 s4, v254, 15
	s_add_i32 s7, s2, s8
	s_max_i32 s3, s7, 8
	v_add_u32_e32 v247, s4, v0
	s_lshl_b32 s4, s28, 2
	s_add_i32 s2, s2, s4
	v_mov_b32_e32 v14, v1
	v_mov_b32_e32 v15, v1
	v_lshlrev_b32_e32 v245, 3, v13
	s_waitcnt vmcnt(2)
	ds_write_b128 v241, v[2:5] offset:26624
	s_sub_i32 s2, s2, s9
	s_sub_i32 s41, s3, s9
	v_mov_b32_e32 v0, v1
	v_mov_b32_e32 v2, v1
	v_mov_b32_e32 v3, v1
	v_mov_b32_e32 v4, v1
	v_mov_b32_e32 v5, v1
	v_mov_b32_e32 v6, v1
	v_mov_b32_e32 v7, v1
	v_mov_b32_e32 v8, v1
	v_mov_b32_e32 v9, v1
	v_mov_b32_e32 v10, v1
	v_mov_b32_e32 v11, v1
	v_mov_b32_e32 v12, v1
	v_mov_b32_e32 v13, v1
	v_mov_b64_e32 v[46:47], v[14:15]
	v_mov_b64_e32 v[30:31], v[14:15]
	v_mov_b64_e32 v[62:63], v[14:15]
	s_add_i32 s6, s3, -8
	s_mov_b32 s29, 0
	v_cmp_eq_u32_e64 s[0:1], 0, v206
	v_add_u32_e32 v246, s26, v250
	s_add_i32 s38, s2, 28
	s_add_i32 s39, s41, -8
	s_add_i32 s41, s41, -9
	v_mov_b32_e32 v222, 0
	v_mov_b64_e32 v[44:45], v[12:13]
	v_mov_b64_e32 v[42:43], v[10:11]
	v_mov_b64_e32 v[40:41], v[8:9]
	v_mov_b64_e32 v[38:39], v[6:7]
	v_mov_b64_e32 v[36:37], v[4:5]
	v_mov_b64_e32 v[34:35], v[2:3]
	v_mov_b64_e32 v[32:33], v[0:1]
	v_mov_b64_e32 v[28:29], v[12:13]
	v_mov_b64_e32 v[26:27], v[10:11]
	v_mov_b64_e32 v[24:25], v[8:9]
	v_mov_b64_e32 v[22:23], v[6:7]
	v_mov_b64_e32 v[20:21], v[4:5]
	v_mov_b64_e32 v[18:19], v[2:3]
	v_mov_b64_e32 v[16:17], v[0:1]
	v_mov_b64_e32 v[60:61], v[12:13]
	v_mov_b64_e32 v[58:59], v[10:11]
	v_mov_b64_e32 v[56:57], v[8:9]
	v_mov_b64_e32 v[54:55], v[6:7]
	v_mov_b64_e32 v[52:53], v[4:5]
	v_mov_b64_e32 v[50:51], v[2:3]
	v_mov_b64_e32 v[48:49], v[0:1]
	v_mov_b32_e32 v225, 0
	s_waitcnt lgkmcnt(0)
	s_barrier
	s_branch .LBB0_607

; __device__ __forceinline__ int crow(int r, int hi) { return (r & 3) + 8 * (r >> 2) + 4 * hi; }
; #define ATT_LOAD(t, S) do { const int tl_ = (t) < u_hi ? (t) : u_hi;     \
;         k##S = *(const u32x4*)(kg + (size_t)tl_ * 64 * 512); v##S = *(const u32x4*)(vg + (size_t)tl_ * 64 * 512); \
;         if (TYPE == 1) k2##S = *(const u32x4*)(krg + (size_t)tl_ * 64 * 32); if (TYPE == 0) cb##S = cg_[tl_ * 64]; } while (0)
; template <int TYPE, int ND0, int KSTR> __device__ __forceinline__ void tile(LAS unsigned char* lds, int buf, int t, int w_lo, int w_hi, int n, int qrel, int lane, int r32, int hi,
;         const bf16x8 (&qr)[ND0], float& m_run, float& l_run, f32x16& o0, f32x16& o1, f32x16& negm) {
;     ...
;         if (t == w_hi) {
; #pragma unroll
;             for (int r = 0; r < 16; ++r) { const int kr_ = crow(r, hi); if (kr_ > qrel) p0[r] = -1e30f; if (kr_ + 32 > qrel) p1[r] = -1e30f; }
;         }
; template <int TYPE> __device__ __forceinline__ int unit(const P& p, LAS unsigned char* lds, int b, int h, int qb, int wave0, bool pre, unsigned nx, int G,
;         u32x4& kA, u32x4& vA, u32x4& k2A, float& cbA, u32x4& kB, u32x4& vB, u32x4& k2B, float& cbB) {
;     ...
;     float m_run = 0.f, l_run = 0.f; f32x16 o0 = {}, o1 = {};
;     f32x16 negm;
; #pragma unroll
;     for (int r = 0; r < 16; ++r) negm[r] = 0.f;
;     if (!pre) { ATT_LOAD(u_lo, A); ATT_LOAD(u_lo + 1, B); }
;     ATT_STORE(0, A);
;     __syncthreads();
;     const int qrel = 32 * (w & 1) + r32;
;     int t = u_lo;
;     for (; t < u_hi - 1; t += 2) {
.LBB0_656:
	s_or_b64 exec, exec, s[0:1]
	v_lshrrev_b32_e32 v244, 2, v230
	v_lshlrev_b32_e32 v218, 2, v13
	v_and_or_b32 v2, v244, 3, v218
	s_waitcnt vmcnt(2)
	v_mad_u32_u24 v239, v2, s27, 0
	v_and_b32_e32 v2, 16, v230
	v_and_or_b32 v2, v180, 12, v2
	v_and_or_b32 v0, s2, 32, v12
	v_lshlrev_b32_e32 v243, 1, v2
	v_or_b32_e32 v2, 32, v218
	v_cmp_gt_u32_e64 s[46:47], v2, v0
	v_or_b32_e32 v2, 33, v218
	v_cmp_gt_u32_e64 s[48:49], v2, v0
	v_or_b32_e32 v2, 2, v218
	v_cmp_gt_u32_e64 s[50:51], v2, v0
	v_or_b32_e32 v2, 34, v218
	v_cmp_gt_u32_e64 s[52:53], v2, v0
	v_or_b32_e32 v2, 3, v218
	v_cmp_gt_u32_e64 s[54:55], v2, v0
	v_or_b32_e32 v2, 35, v218
	v_cmp_gt_u32_e64 s[56:57], v2, v0
	v_or_b32_e32 v2, 8, v218
	v_cmp_gt_u32_e64 s[58:59], v2, v0
	v_or_b32_e32 v2, 40, v218
	v_cmp_gt_u32_e64 s[60:61], v2, v0
	v_or_b32_e32 v2, 9, v218
	v_cmp_gt_u32_e64 s[62:63], v2, v0
	v_or_b32_e32 v2, 41, v218
	v_cmp_gt_u32_e64 s[64:65], v2, v0
	v_or_b32_e32 v2, 10, v218
	v_cmp_gt_u32_e64 s[66:67], v2, v0
	v_or_b32_e32 v2, 42, v218
	v_cmp_gt_u32_e64 s[68:69], v2, v0
	v_or_b32_e32 v2, 11, v218
	v_cmp_gt_u32_e64 s[70:71], v2, v0
	v_or_b32_e32 v2, 43, v218
	v_cmp_gt_u32_e64 s[74:75], v2, v0
	v_or_b32_e32 v2, 16, v218
	v_cmp_gt_u32_e64 s[76:77], v2, v0
	v_or_b32_e32 v2, 48, v218
	v_cmp_gt_u32_e64 s[78:79], v2, v0
	v_or_b32_e32 v2, 17, v218
	v_cmp_gt_u32_e64 s[80:81], v2, v0
	v_or_b32_e32 v2, 49, v218
	v_cmp_gt_u32_e64 s[82:83], v2, v0
	v_or_b32_e32 v2, 18, v218
	v_cmp_gt_u32_e64 s[84:85], v2, v0
	v_or_b32_e32 v2, 50, v218
	v_cmp_gt_u32_e64 s[86:87], v2, v0
	v_or_b32_e32 v2, 19, v218
	v_cmp_gt_u32_e64 s[88:89], v2, v0
	v_or_b32_e32 v2, 51, v218
	v_cmp_gt_u32_e64 s[90:91], v2, v0
	v_or_b32_e32 v2, 24, v218
	v_cmp_gt_u32_e64 s[92:93], v2, v0
	v_or_b32_e32 v2, 56, v218
	v_cmp_gt_u32_e64 s[94:95], v2, v0
	v_or_b32_e32 v2, 25, v218
	s_movk_i32 s0, 0x90
	v_cmp_gt_u32_e64 s[96:97], v2, v0
	v_or_b32_e32 v2, 57, v218
	v_mad_u32_u24 v173, v12, s0, 0
	v_cmp_gt_u32_e64 s[0:1], v2, v0
	v_or_b32_e32 v2, 26, v218
	v_cmp_gt_u32_e64 s[4:5], v2, v0
	v_or_b32_e32 v2, 58, v218
	v_cmp_gt_u32_e64 s[6:7], v2, v0
	v_or_b32_e32 v2, 27, v218
	v_lshlrev_b32_e32 v245, 3, v14
	s_ashr_i32 s3, s3, 7
	s_lshl_b32 s25, s33, 2
	v_cmp_gt_u32_e64 s[8:9], v2, v0
	v_or_b32_e32 v2, 59, v218
	s_lshl_b32 s2, s28, 2
	v_mov_b32_e32 v14, v1
	v_mov_b32_e32 v15, v1
	v_lshlrev_b64 v[176:177], 9, v[10:11]
	s_add_i32 s41, s3, s25
	v_cmp_gt_u32_e64 s[42:43], v218, v0
	v_cmp_lt_u32_e64 s[38:39], v218, v0
	v_cmp_gt_u32_e64 s[72:73], v2, v0
	s_add_i32 s3, s3, s2
	v_mov_b32_e32 v0, v1
	v_mov_b32_e32 v2, v1
	v_mov_b32_e32 v3, v1
	v_mov_b32_e32 v4, v1
	v_mov_b32_e32 v5, v1
	v_mov_b32_e32 v6, v1
	v_mov_b32_e32 v7, v1
	v_mov_b32_e32 v8, v1
	v_mov_b32_e32 v9, v1
	v_mov_b32_e32 v10, v1
	v_mov_b32_e32 v11, v1
	v_mov_b32_e32 v12, v1
	v_mov_b32_e32 v13, v1
	v_mov_b64_e32 v[46:47], v[14:15]
	v_mov_b64_e32 v[30:31], v[14:15]
	v_mov_b64_e32 v[62:63], v[14:15]
	v_add_u32_e32 v231, 0, v172
	v_add_u32_e32 v246, s26, v250
	s_mov_b32 s28, 0
	s_sub_i32 s30, 0, s3
	v_mov_b32_e32 v178, 0
	s_mov_b32 s29, -2
	v_mov_b64_e32 v[44:45], v[12:13]
	v_mov_b64_e32 v[42:43], v[10:11]
	v_mov_b64_e32 v[40:41], v[8:9]
	v_mov_b64_e32 v[38:39], v[6:7]
	v_mov_b64_e32 v[36:37], v[4:5]
	v_mov_b64_e32 v[34:35], v[2:3]
	v_mov_b64_e32 v[32:33], v[0:1]
	v_mov_b64_e32 v[28:29], v[12:13]
	v_mov_b64_e32 v[26:27], v[10:11]
	v_mov_b64_e32 v[24:25], v[8:9]
	v_mov_b64_e32 v[22:23], v[6:7]
	v_mov_b64_e32 v[20:21], v[4:5]
	v_mov_b64_e32 v[18:19], v[2:3]
	v_mov_b64_e32 v[16:17], v[0:1]
	v_mov_b64_e32 v[60:61], v[12:13]
	v_mov_b64_e32 v[58:59], v[10:11]
	v_mov_b64_e32 v[56:57], v[8:9]
	v_mov_b64_e32 v[54:55], v[6:7]
	v_mov_b64_e32 v[52:53], v[4:5]
	v_mov_b64_e32 v[50:51], v[2:3]
	v_mov_b64_e32 v[48:49], v[0:1]
	v_mov_b32_e32 v181, 0
	s_waitcnt lgkmcnt(0)
	s_barrier

; #define ATT_LOAD(t, S) do { const int tl_ = (t) < u_hi ? (t) : u_hi;     \
;         k##S = *(const u32x4*)(kg + (size_t)tl_ * 64 * 512); v##S = *(const u32x4*)(vg + (size_t)tl_ * 64 * 512); \
;         if (TYPE == 1) k2##S = *(const u32x4*)(krg + (size_t)tl_ * 64 * 32); if (TYPE == 0) cb##S = cg_[tl_ * 64]; } while (0)
; template <int TYPE> __device__ __forceinline__ int unit(const P& p, LAS unsigned char* lds, int b, int h, int qb, int wave0, bool pre, unsigned nx, int G,
;         u32x4& kA, u32x4& vA, u32x4& k2A, float& cbA, u32x4& kB, u32x4& vB, u32x4& k2B, float& cbB) {
;     ...
;     float m_run = 0.f, l_run = 0.f; f32x16 o0 = {}, o1 = {};
;     f32x16 negm;
; #pragma unroll
;     for (int r = 0; r < 16; ++r) negm[r] = 0.f;
;     if (!pre) { ATT_LOAD(u_lo, A); ATT_LOAD(u_lo + 1, B); }
;     ATT_STORE(0, A);
;     __syncthreads();
;     const int qrel = 32 * (w & 1) + r32;
;     int t = u_lo;
;     for (; t < u_hi - 1; t += 2) {
.LBB0_703:
	s_or_b64 exec, exec, s[4:5]
	v_lshlrev_b32_e32 v218, 2, v3
	v_and_b32_e32 v178, 63, v226
	v_mad_u32_u24 v227, v2, s10, 0
	v_and_or_b32 v2, v6, 3, v218
	s_movk_i32 s4, 0xc0
	v_mad_u32_u24 v228, v2, s4, 0
	v_and_b32_e32 v2, 16, v226
	v_lshlrev_b32_e32 v3, 2, v178
	v_and_or_b32 v2, v3, 12, v2
	v_mov_b32_e32 v14, v1
	v_mov_b32_e32 v15, v1
	v_lshlrev_b32_e32 v231, 3, v4
	v_lshlrev_b32_e32 v230, 3, v5
	s_ashr_i32 s9, s2, 7
	s_lshl_b32 s2, s33, 2
	v_lshlrev_b32_e32 v229, 1, v2
	v_add_u32_e32 v225, 0, v0
	v_mov_b32_e32 v0, v1
	v_mov_b32_e32 v2, v1
	v_mov_b32_e32 v3, v1
	v_mov_b32_e32 v4, v1
	v_mov_b32_e32 v5, v1
	v_mov_b32_e32 v6, v1
	v_mov_b32_e32 v7, v1
	v_mov_b32_e32 v8, v1
	v_mov_b32_e32 v9, v1
	v_mov_b32_e32 v10, v1
	v_mov_b32_e32 v11, v1
	v_mov_b32_e32 v12, v1
	v_mov_b32_e32 v13, v1
	v_mov_b64_e32 v[46:47], v[14:15]
	v_mov_b64_e32 v[30:31], v[14:15]
	v_mov_b64_e32 v[62:63], v[14:15]
	s_lshl_b32 s8, s24, 6
	s_add_i32 s9, s9, s2
	v_add_u32_e32 v219, s26, v250
	s_mov_b32 s3, 0
	v_mov_b32_e32 v166, 0
	v_mov_b64_e32 v[44:45], v[12:13]
	v_mov_b64_e32 v[42:43], v[10:11]
	v_mov_b64_e32 v[40:41], v[8:9]
	v_mov_b64_e32 v[38:39], v[6:7]
	v_mov_b64_e32 v[36:37], v[4:5]
	v_mov_b64_e32 v[34:35], v[2:3]
	v_mov_b64_e32 v[32:33], v[0:1]
	v_mov_b64_e32 v[28:29], v[12:13]
	v_mov_b64_e32 v[26:27], v[10:11]
	v_mov_b64_e32 v[24:25], v[8:9]
	v_mov_b64_e32 v[22:23], v[6:7]
	v_mov_b64_e32 v[20:21], v[4:5]
	v_mov_b64_e32 v[18:19], v[2:3]
	v_mov_b64_e32 v[16:17], v[0:1]
	v_mov_b64_e32 v[60:61], v[12:13]
	v_mov_b64_e32 v[58:59], v[10:11]
	v_mov_b64_e32 v[56:57], v[8:9]
	v_mov_b64_e32 v[54:55], v[6:7]
	v_mov_b64_e32 v[52:53], v[4:5]
	v_mov_b64_e32 v[50:51], v[2:3]
	v_mov_b64_e32 v[48:49], v[0:1]
	v_mov_b32_e32 v171, 0
	s_waitcnt lgkmcnt(0)
	s_barrier
